# GLU epilogue rewritten: packed f32 math, one reciprocal per element ((a*z)*rcp((1+e^-b)(1+e^-z))), f32 throughout; on top of packed S3 epilogue
# baseline (speedup 1.0000x reference)
; __device__ __forceinline__ unsigned cvt_pk_bf16(float lo, float hi) { unsigned r; asm volatile("v_cvt_pk_bf16_f32 %0, %1, %2" : "=v"(r) : "v"(lo), "v"(hi)); return r; }
; __device__ __forceinline__ float bflo(unsigned w) { return __uint_as_float(w << 16); }
; __device__ __forceinline__ float bfhi(unsigned w) { return __uint_as_float(w & 0xffff0000u); }
; __device__ __forceinline__ float silu_f(float z) { return z / (1.0f + __expf(-z)); }
; __device__ __forceinline__ float sigmoid_f(float z) { return 1.0f / (1.0f + __expf(-z)); }
;     __device__ __forceinline__ void operator()(const AccT& acc, const Unit& u, int wr, int wc, int fr, int fq) const {
;         bf16_t* OCAT = (bf16_t*)(ws + WS_H); const bf16_t* PROJ = (const bf16_t*)(ws + WS_PROJ);
;         const int lc = u.pn * 128 + wc * 32 + 8 * fq;
;         const f32x4 bl0 = *(const f32x4*)(bglu + lc), bl1 = *(const f32x4*)(bglu + lc + 4), bg0 = *(const f32x4*)(bglu + 1024 + lc), bg1 = *(const f32x4*)(bglu + 1024 + lc + 4);
; #pragma unroll
;         for (int ai = 0; ai < 2; ++ai)
; #pragma unroll
;             for (int m = 0; m < 4; ++m) {
;                 const int row = u.pm * 256 + ai * 128 + wr * 64 + m * 16 + fr;
;                 const u32x4 z = *(const u32x4*)(PROJ + (size_t)row * PP + C_ZS + lc);
;                 const f32x4 l0 = acc[ai][0][m][0] + bl0, l1 = acc[ai][0][m][1] + bl1, g0 = acc[ai][1][m][0] + bg0, g1 = acc[ai][1][m][1] + bg1;
;                 float o[8];
;                 o[0] = l0[0] * sigmoid_f(g0[0]) * silu_f(bflo(z.x)); o[1] = l0[1] * sigmoid_f(g0[1]) * silu_f(bfhi(z.x));
;                 o[2] = l0[2] * sigmoid_f(g0[2]) * silu_f(bflo(z.y)); o[3] = l0[3] * sigmoid_f(g0[3]) * silu_f(bfhi(z.y));
;                 o[4] = l1[0] * sigmoid_f(g1[0]) * silu_f(bflo(z.z)); o[5] = l1[1] * sigmoid_f(g1[1]) * silu_f(bfhi(z.z));
;                 o[6] = l1[2] * sigmoid_f(g1[2]) * silu_f(bflo(z.w)); o[7] = l1[3] * sigmoid_f(g1[3]) * silu_f(bfhi(z.w));
;                 u32x4 w; w.x = cvt_pk_bf16(o[0], o[1]); w.y = cvt_pk_bf16(o[2], o[3]); w.z = cvt_pk_bf16(o[4], o[5]); w.w = cvt_pk_bf16(o[6], o[7]);
;                 *(u32x4*)(OCAT + (size_t)row * 2048 + 1024 + lc) = w;
;                 if (m == 3) asm volatile("" ::: "memory");
;             }
.LBB0_609:
	v_lshl_or_b32 v128, s38, 7, v166
	v_ashrrev_i32_e32 v129, 31, v128
	v_lshl_add_u32 v168, s37, 8, v164
	v_mov_b64_e32 v[160:161], s[6:7]
	v_lshlrev_b64 v[16:17], 2, v[128:129]
	v_mad_i64_i32 v[162:163], s[30:31], v168, s52, v[160:161]
	v_lshlrev_b64 v[158:159], 1, v[128:129]
	v_lshl_add_u64 v[18:19], s[16:17], 0, v[16:17]
	v_lshl_add_u64 v[20:21], s[18:19], 0, v[16:17]
	v_lshl_add_u64 v[128:129], v[162:163], 0, v[158:159]
	global_load_dwordx4 v[24:27], v[18:19], off offset:16
	global_load_dwordx4 v[28:31], v[18:19], off
	s_nop 0
	global_load_dwordx4 v[16:19], v[20:21], off offset:16
	s_nop 0
	global_load_dwordx4 v[20:23], v[20:21], off
	v_add_co_u32_e32 v128, vcc, s63, v128
	s_nop 1
	v_addc_co_u32_e32 v129, vcc, 0, v129, vcc
	s_mov_b32 s82, 0x28000
	s_mov_b32 s83, 0
	v_lshl_add_u64 v[180:181], v[128:129], 0, s[82:83]
	s_mov_b32 s82, 0x50000
	s_mov_b32 s83, 0
	v_lshl_add_u64 v[184:185], v[128:129], 0, s[82:83]
	s_mov_b32 s82, 0x78000
	s_mov_b32 s83, 0
	v_lshl_add_u64 v[188:189], v[128:129], 0, s[82:83]
	s_mov_b32 s82, 0x140000
	s_mov_b32 s83, 0
	v_lshl_add_u64 v[192:193], v[128:129], 0, s[82:83]
	s_mov_b32 s82, 0x168000
	s_mov_b32 s83, 0
	v_lshl_add_u64 v[196:197], v[128:129], 0, s[82:83]
	s_mov_b32 s82, 0x190000
	s_mov_b32 s83, 0
	v_lshl_add_u64 v[200:201], v[128:129], 0, s[82:83]
	s_mov_b32 s82, 0x1b8000
	s_mov_b32 s83, 0
	v_lshl_add_u64 v[204:205], v[128:129], 0, s[82:83]
	global_load_dwordx4 v[176:179], v[128:129], off
	global_load_dwordx4 v[180:183], v[180:181], off
	global_load_dwordx4 v[184:187], v[184:185], off
	global_load_dwordx4 v[188:191], v[188:189], off
	global_load_dwordx4 v[192:195], v[192:193], off
	global_load_dwordx4 v[196:199], v[196:197], off
	global_load_dwordx4 v[200:203], v[200:201], off
	global_load_dwordx4 v[204:207], v[204:205], off
	v_mov_b32_e32 v208, 0xbfb8aa3b
	v_mov_b32_e32 v209, 0xbfb8aa3b
	s_waitcnt vmcnt(7)
	v_pk_add_f32 v[144:145], v[144:145], v[28:29]
	v_pk_add_f32 v[146:147], v[146:147], v[30:31]
	v_pk_add_f32 v[140:141], v[140:141], v[24:25]
	v_pk_add_f32 v[142:143], v[142:143], v[26:27]
	v_pk_add_f32 v[136:137], v[136:137], v[20:21]
	v_pk_add_f32 v[138:139], v[138:139], v[22:23]
	v_pk_add_f32 v[132:133], v[132:133], v[16:17]
	v_pk_add_f32 v[134:135], v[134:135], v[18:19]
	v_pk_mul_f32 v[136:137], v[136:137], v[208:209]
	v_pk_mul_f32 v[138:139], v[138:139], v[208:209]
	v_pk_mul_f32 v[132:133], v[132:133], v[208:209]
	v_pk_mul_f32 v[134:135], v[134:135], v[208:209]
	v_lshlrev_b32_e32 v210, 16, v176
	v_and_b32_e32 v211, 0xffff0000, v176
	v_lshlrev_b32_e32 v212, 16, v177
	v_and_b32_e32 v213, 0xffff0000, v177
	v_lshlrev_b32_e32 v214, 16, v178
	v_and_b32_e32 v215, 0xffff0000, v178
	v_lshlrev_b32_e32 v216, 16, v179
	v_and_b32_e32 v217, 0xffff0000, v179
	v_pk_mul_f32 v[218:219], v[210:211], v[208:209]
	v_pk_mul_f32 v[220:221], v[212:213], v[208:209]
	v_pk_mul_f32 v[222:223], v[214:215], v[208:209]
	v_pk_mul_f32 v[226:227], v[216:217], v[208:209]
	v_exp_f32_e32 v136, v136
	v_exp_f32_e32 v137, v137
	v_exp_f32_e32 v138, v138
	v_exp_f32_e32 v139, v139
	v_exp_f32_e32 v132, v132
	v_exp_f32_e32 v133, v133
	v_exp_f32_e32 v134, v134
	v_exp_f32_e32 v135, v135
	v_exp_f32_e32 v218, v218
	v_exp_f32_e32 v219, v219
	v_exp_f32_e32 v220, v220
	v_exp_f32_e32 v221, v221
	v_exp_f32_e32 v222, v222
	v_exp_f32_e32 v223, v223
	v_exp_f32_e32 v226, v226
	v_exp_f32_e32 v227, v227
	v_mad_i64_i32 v[174:175], s[30:31], v168, s66, v[162:163]
	v_lshl_add_u64 v[174:175], v[174:175], 0, v[158:159]
	v_add_co_u32_e32 v174, vcc, s67, v174
	s_nop 1
	v_addc_co_u32_e32 v175, vcc, 0, v175, vcc
	v_pk_add_f32 v[136:137], v[136:137], 1.0 op_sel_hi:[1,0]
	v_pk_add_f32 v[138:139], v[138:139], 1.0 op_sel_hi:[1,0]
	v_pk_add_f32 v[132:133], v[132:133], 1.0 op_sel_hi:[1,0]
	v_pk_add_f32 v[134:135], v[134:135], 1.0 op_sel_hi:[1,0]
	v_pk_add_f32 v[218:219], v[218:219], 1.0 op_sel_hi:[1,0]
	v_pk_add_f32 v[220:221], v[220:221], 1.0 op_sel_hi:[1,0]
	v_pk_add_f32 v[222:223], v[222:223], 1.0 op_sel_hi:[1,0]
	v_pk_add_f32 v[226:227], v[226:227], 1.0 op_sel_hi:[1,0]
	v_pk_mul_f32 v[218:219], v[218:219], v[136:137]
	v_pk_mul_f32 v[220:221], v[220:221], v[138:139]
	v_pk_mul_f32 v[222:223], v[222:223], v[132:133]
	v_pk_mul_f32 v[226:227], v[226:227], v[134:135]
	v_rcp_f32_e32 v218, v218
	v_rcp_f32_e32 v219, v219
	v_rcp_f32_e32 v220, v220
	v_rcp_f32_e32 v221, v221
	v_rcp_f32_e32 v222, v222
	v_rcp_f32_e32 v223, v223
	v_rcp_f32_e32 v226, v226
	v_rcp_f32_e32 v227, v227
	v_pk_mul_f32 v[144:145], v[144:145], v[210:211]
	v_pk_mul_f32 v[146:147], v[146:147], v[212:213]
	v_pk_mul_f32 v[140:141], v[140:141], v[214:215]
	v_pk_mul_f32 v[142:143], v[142:143], v[216:217]
	v_pk_mul_f32 v[144:145], v[144:145], v[218:219]
	v_pk_mul_f32 v[146:147], v[146:147], v[220:221]
	v_pk_mul_f32 v[140:141], v[140:141], v[222:223]
	v_pk_mul_f32 v[142:143], v[142:143], v[226:227]
	v_cvt_pk_bf16_f32 v132, v144, v145
	v_cvt_pk_bf16_f32 v133, v146, v147
	v_cvt_pk_bf16_f32 v134, v140, v141
	v_cvt_pk_bf16_f32 v135, v142, v143
	global_store_dwordx4 v[174:175], v[132:135], off offset:2048
	s_waitcnt vmcnt(7)
; __device__ __forceinline__ unsigned cvt_pk_bf16(float lo, float hi) { unsigned r; asm volatile("v_cvt_pk_bf16_f32 %0, %1, %2" : "=v"(r) : "v"(lo), "v"(hi)); return r; }
; __device__ __forceinline__ float bflo(unsigned w) { return __uint_as_float(w << 16); }
; __device__ __forceinline__ float bfhi(unsigned w) { return __uint_as_float(w & 0xffff0000u); }
; __device__ __forceinline__ float silu_f(float z) { return z / (1.0f + __expf(-z)); }
; __device__ __forceinline__ float sigmoid_f(float z) { return 1.0f / (1.0f + __expf(-z)); }
;     __device__ __forceinline__ void operator()(const AccT& acc, const Unit& u, int wr, int wc, int fr, int fq) const {
;     ...
;                 const int row = u.pm * 256 + ai * 128 + wr * 64 + m * 16 + fr;
;                 const u32x4 z = *(const u32x4*)(PROJ + (size_t)row * PP + C_ZS + lc);
;                 const f32x4 l0 = acc[ai][0][m][0] + bl0, l1 = acc[ai][0][m][1] + bl1, g0 = acc[ai][1][m][0] + bg0, g1 = acc[ai][1][m][1] + bg1;
;                 float o[8];
;                 o[0] = l0[0] * sigmoid_f(g0[0]) * silu_f(bflo(z.x)); o[1] = l0[1] * sigmoid_f(g0[1]) * silu_f(bfhi(z.x));
;                 o[2] = l0[2] * sigmoid_f(g0[2]) * silu_f(bflo(z.y)); o[3] = l0[3] * sigmoid_f(g0[3]) * silu_f(bfhi(z.y));
;                 o[4] = l1[0] * sigmoid_f(g1[0]) * silu_f(bflo(z.z)); o[5] = l1[1] * sigmoid_f(g1[1]) * silu_f(bfhi(z.z));
;                 o[6] = l1[2] * sigmoid_f(g1[2]) * silu_f(bflo(z.w)); o[7] = l1[3] * sigmoid_f(g1[3]) * silu_f(bfhi(z.w));
;                 u32x4 w; w.x = cvt_pk_bf16(o[0], o[1]); w.y = cvt_pk_bf16(o[2], o[3]); w.z = cvt_pk_bf16(o[4], o[5]); w.w = cvt_pk_bf16(o[6], o[7]);
;                 *(u32x4*)(OCAT + (size_t)row * 2048 + 1024 + lc) = w;
	v_pk_add_f32 v[124:125], v[124:125], v[28:29]
	v_pk_add_f32 v[126:127], v[126:127], v[30:31]
	v_pk_add_f32 v[120:121], v[120:121], v[24:25]
	v_pk_add_f32 v[122:123], v[122:123], v[26:27]
	v_pk_add_f32 v[116:117], v[116:117], v[20:21]
	v_pk_add_f32 v[118:119], v[118:119], v[22:23]
	v_pk_add_f32 v[112:113], v[112:113], v[16:17]
	v_pk_add_f32 v[114:115], v[114:115], v[18:19]
	v_pk_mul_f32 v[116:117], v[116:117], v[208:209]
	v_pk_mul_f32 v[118:119], v[118:119], v[208:209]
	v_pk_mul_f32 v[112:113], v[112:113], v[208:209]
	v_pk_mul_f32 v[114:115], v[114:115], v[208:209]
	v_lshlrev_b32_e32 v210, 16, v180
	v_and_b32_e32 v211, 0xffff0000, v180
	v_lshlrev_b32_e32 v212, 16, v181
	v_and_b32_e32 v213, 0xffff0000, v181
	v_lshlrev_b32_e32 v214, 16, v182
	v_and_b32_e32 v215, 0xffff0000, v182
	v_lshlrev_b32_e32 v216, 16, v183
	v_and_b32_e32 v217, 0xffff0000, v183
	v_pk_mul_f32 v[218:219], v[210:211], v[208:209]
	v_pk_mul_f32 v[220:221], v[212:213], v[208:209]
	v_pk_mul_f32 v[222:223], v[214:215], v[208:209]
	v_pk_mul_f32 v[226:227], v[216:217], v[208:209]
	v_exp_f32_e32 v116, v116
	v_exp_f32_e32 v117, v117
	v_exp_f32_e32 v118, v118
	v_exp_f32_e32 v119, v119
	v_exp_f32_e32 v112, v112
	v_exp_f32_e32 v113, v113
	v_exp_f32_e32 v114, v114
	v_exp_f32_e32 v115, v115
	v_exp_f32_e32 v218, v218
	v_exp_f32_e32 v219, v219
	v_exp_f32_e32 v220, v220
	v_exp_f32_e32 v221, v221
	v_exp_f32_e32 v222, v222
	v_exp_f32_e32 v223, v223
	v_exp_f32_e32 v226, v226
	v_exp_f32_e32 v227, v227
	v_or_b32_e32 v170, 16, v168
	v_mad_i64_i32 v[172:173], s[30:31], v170, s52, v[160:161]
	v_mad_i64_i32 v[174:175], s[30:31], v170, s66, v[172:173]
	v_lshl_add_u64 v[174:175], v[174:175], 0, v[158:159]
	v_add_co_u32_e32 v174, vcc, s67, v174
	s_nop 1
	v_addc_co_u32_e32 v175, vcc, 0, v175, vcc
	v_pk_add_f32 v[116:117], v[116:117], 1.0 op_sel_hi:[1,0]
	v_pk_add_f32 v[118:119], v[118:119], 1.0 op_sel_hi:[1,0]
	v_pk_add_f32 v[112:113], v[112:113], 1.0 op_sel_hi:[1,0]
	v_pk_add_f32 v[114:115], v[114:115], 1.0 op_sel_hi:[1,0]
	v_pk_add_f32 v[218:219], v[218:219], 1.0 op_sel_hi:[1,0]
	v_pk_add_f32 v[220:221], v[220:221], 1.0 op_sel_hi:[1,0]
	v_pk_add_f32 v[222:223], v[222:223], 1.0 op_sel_hi:[1,0]
	v_pk_add_f32 v[226:227], v[226:227], 1.0 op_sel_hi:[1,0]
	v_pk_mul_f32 v[218:219], v[218:219], v[116:117]
	v_pk_mul_f32 v[220:221], v[220:221], v[118:119]
	v_pk_mul_f32 v[222:223], v[222:223], v[112:113]
	v_pk_mul_f32 v[226:227], v[226:227], v[114:115]
	v_rcp_f32_e32 v218, v218
	v_rcp_f32_e32 v219, v219
	v_rcp_f32_e32 v220, v220
	v_rcp_f32_e32 v221, v221
	v_rcp_f32_e32 v222, v222
	v_rcp_f32_e32 v223, v223
	v_rcp_f32_e32 v226, v226
	v_rcp_f32_e32 v227, v227
	v_pk_mul_f32 v[124:125], v[124:125], v[210:211]
	v_pk_mul_f32 v[126:127], v[126:127], v[212:213]
	v_pk_mul_f32 v[120:121], v[120:121], v[214:215]
	v_pk_mul_f32 v[122:123], v[122:123], v[216:217]
	v_pk_mul_f32 v[124:125], v[124:125], v[218:219]
	v_pk_mul_f32 v[126:127], v[126:127], v[220:221]
	v_pk_mul_f32 v[120:121], v[120:121], v[222:223]
	v_pk_mul_f32 v[122:123], v[122:123], v[226:227]
	v_cvt_pk_bf16_f32 v112, v124, v125
	v_cvt_pk_bf16_f32 v113, v126, v127
	v_cvt_pk_bf16_f32 v114, v120, v121
	v_cvt_pk_bf16_f32 v115, v122, v123
	global_store_dwordx4 v[174:175], v[112:115], off offset:2048
	s_waitcnt vmcnt(7)
	v_pk_add_f32 v[108:109], v[108:109], v[28:29]
	v_pk_add_f32 v[110:111], v[110:111], v[30:31]
	v_pk_add_f32 v[104:105], v[104:105], v[24:25]
	v_pk_add_f32 v[106:107], v[106:107], v[26:27]
	v_pk_add_f32 v[100:101], v[100:101], v[20:21]
	v_pk_add_f32 v[102:103], v[102:103], v[22:23]
	v_pk_add_f32 v[96:97], v[96:97], v[16:17]
	v_pk_add_f32 v[98:99], v[98:99], v[18:19]
	v_pk_mul_f32 v[100:101], v[100:101], v[208:209]
	v_pk_mul_f32 v[102:103], v[102:103], v[208:209]
	v_pk_mul_f32 v[96:97], v[96:97], v[208:209]
	v_pk_mul_f32 v[98:99], v[98:99], v[208:209]
	v_lshlrev_b32_e32 v210, 16, v184
	v_and_b32_e32 v211, 0xffff0000, v184
	v_lshlrev_b32_e32 v212, 16, v185
	v_and_b32_e32 v213, 0xffff0000, v185
	v_lshlrev_b32_e32 v214, 16, v186
	v_and_b32_e32 v215, 0xffff0000, v186
	v_lshlrev_b32_e32 v216, 16, v187
	v_and_b32_e32 v217, 0xffff0000, v187
	v_pk_mul_f32 v[218:219], v[210:211], v[208:209]
	v_pk_mul_f32 v[220:221], v[212:213], v[208:209]
	v_pk_mul_f32 v[222:223], v[214:215], v[208:209]
	v_pk_mul_f32 v[226:227], v[216:217], v[208:209]
	v_exp_f32_e32 v100, v100
	v_exp_f32_e32 v101, v101
	v_exp_f32_e32 v102, v102
	v_exp_f32_e32 v103, v103
	v_exp_f32_e32 v96, v96
	v_exp_f32_e32 v97, v97
	v_exp_f32_e32 v98, v98
	v_exp_f32_e32 v99, v99
	v_exp_f32_e32 v218, v218
	v_exp_f32_e32 v219, v219
	v_exp_f32_e32 v220, v220
	v_exp_f32_e32 v221, v221
	v_exp_f32_e32 v222, v222
	v_exp_f32_e32 v223, v223
	v_exp_f32_e32 v226, v226
	v_exp_f32_e32 v227, v227
	v_or_b32_e32 v170, 32, v168
	v_mad_i64_i32 v[172:173], s[30:31], v170, s52, v[160:161]
	v_mad_i64_i32 v[174:175], s[30:31], v170, s66, v[172:173]
	v_lshl_add_u64 v[174:175], v[174:175], 0, v[158:159]
	v_add_co_u32_e32 v174, vcc, s67, v174
	s_nop 1
	v_addc_co_u32_e32 v175, vcc, 0, v175, vcc
	v_pk_add_f32 v[100:101], v[100:101], 1.0 op_sel_hi:[1,0]
	v_pk_add_f32 v[102:103], v[102:103], 1.0 op_sel_hi:[1,0]
	v_pk_add_f32 v[96:97], v[96:97], 1.0 op_sel_hi:[1,0]
	v_pk_add_f32 v[98:99], v[98:99], 1.0 op_sel_hi:[1,0]
	v_pk_add_f32 v[218:219], v[218:219], 1.0 op_sel_hi:[1,0]
	v_pk_add_f32 v[220:221], v[220:221], 1.0 op_sel_hi:[1,0]
	v_pk_add_f32 v[222:223], v[222:223], 1.0 op_sel_hi:[1,0]
	v_pk_add_f32 v[226:227], v[226:227], 1.0 op_sel_hi:[1,0]
	v_pk_mul_f32 v[218:219], v[218:219], v[100:101]
	v_pk_mul_f32 v[220:221], v[220:221], v[102:103]
	v_pk_mul_f32 v[222:223], v[222:223], v[96:97]
	v_pk_mul_f32 v[226:227], v[226:227], v[98:99]
	v_rcp_f32_e32 v218, v218
	v_rcp_f32_e32 v219, v219
	v_rcp_f32_e32 v220, v220
	v_rcp_f32_e32 v221, v221
	v_rcp_f32_e32 v222, v222
	v_rcp_f32_e32 v223, v223
	v_rcp_f32_e32 v226, v226
	v_rcp_f32_e32 v227, v227
	v_pk_mul_f32 v[108:109], v[108:109], v[210:211]
	v_pk_mul_f32 v[110:111], v[110:111], v[212:213]
	v_pk_mul_f32 v[104:105], v[104:105], v[214:215]
	v_pk_mul_f32 v[106:107], v[106:107], v[216:217]
	v_pk_mul_f32 v[108:109], v[108:109], v[218:219]
	v_pk_mul_f32 v[110:111], v[110:111], v[220:221]
	v_pk_mul_f32 v[104:105], v[104:105], v[222:223]
	v_pk_mul_f32 v[106:107], v[106:107], v[226:227]
	v_cvt_pk_bf16_f32 v96, v108, v109
	v_cvt_pk_bf16_f32 v97, v110, v111
	v_cvt_pk_bf16_f32 v98, v104, v105
	v_cvt_pk_bf16_f32 v99, v106, v107
	global_store_dwordx4 v[174:175], v[96:99], off offset:2048
	s_waitcnt vmcnt(7)
; __device__ __forceinline__ unsigned cvt_pk_bf16(float lo, float hi) { unsigned r; asm volatile("v_cvt_pk_bf16_f32 %0, %1, %2" : "=v"(r) : "v"(lo), "v"(hi)); return r; }
; __device__ __forceinline__ float bflo(unsigned w) { return __uint_as_float(w << 16); }
; __device__ __forceinline__ float bfhi(unsigned w) { return __uint_as_float(w & 0xffff0000u); }
; __device__ __forceinline__ float silu_f(float z) { return z / (1.0f + __expf(-z)); }
; __device__ __forceinline__ float sigmoid_f(float z) { return 1.0f / (1.0f + __expf(-z)); }
;     __device__ __forceinline__ void operator()(const AccT& acc, const Unit& u, int wr, int wc, int fr, int fq) const {
;     ...
;                 const int row = u.pm * 256 + ai * 128 + wr * 64 + m * 16 + fr;
;                 const u32x4 z = *(const u32x4*)(PROJ + (size_t)row * PP + C_ZS + lc);
;                 const f32x4 l0 = acc[ai][0][m][0] + bl0, l1 = acc[ai][0][m][1] + bl1, g0 = acc[ai][1][m][0] + bg0, g1 = acc[ai][1][m][1] + bg1;
;                 float o[8];
;                 o[0] = l0[0] * sigmoid_f(g0[0]) * silu_f(bflo(z.x)); o[1] = l0[1] * sigmoid_f(g0[1]) * silu_f(bfhi(z.x));
;                 o[2] = l0[2] * sigmoid_f(g0[2]) * silu_f(bflo(z.y)); o[3] = l0[3] * sigmoid_f(g0[3]) * silu_f(bfhi(z.y));
;                 o[4] = l1[0] * sigmoid_f(g1[0]) * silu_f(bflo(z.z)); o[5] = l1[1] * sigmoid_f(g1[1]) * silu_f(bfhi(z.z));
;                 o[6] = l1[2] * sigmoid_f(g1[2]) * silu_f(bflo(z.w)); o[7] = l1[3] * sigmoid_f(g1[3]) * silu_f(bfhi(z.w));
;                 u32x4 w; w.x = cvt_pk_bf16(o[0], o[1]); w.y = cvt_pk_bf16(o[2], o[3]); w.z = cvt_pk_bf16(o[4], o[5]); w.w = cvt_pk_bf16(o[6], o[7]);
;                 *(u32x4*)(OCAT + (size_t)row * 2048 + 1024 + lc) = w;
	v_pk_add_f32 v[92:93], v[92:93], v[28:29]
	v_pk_add_f32 v[94:95], v[94:95], v[30:31]
	v_pk_add_f32 v[88:89], v[88:89], v[24:25]
	v_pk_add_f32 v[90:91], v[90:91], v[26:27]
	v_pk_add_f32 v[84:85], v[84:85], v[20:21]
	v_pk_add_f32 v[86:87], v[86:87], v[22:23]
	v_pk_add_f32 v[80:81], v[80:81], v[16:17]
	v_pk_add_f32 v[82:83], v[82:83], v[18:19]
	v_pk_mul_f32 v[84:85], v[84:85], v[208:209]
	v_pk_mul_f32 v[86:87], v[86:87], v[208:209]
	v_pk_mul_f32 v[80:81], v[80:81], v[208:209]
	v_pk_mul_f32 v[82:83], v[82:83], v[208:209]
	v_lshlrev_b32_e32 v210, 16, v188
	v_and_b32_e32 v211, 0xffff0000, v188
	v_lshlrev_b32_e32 v212, 16, v189
	v_and_b32_e32 v213, 0xffff0000, v189
	v_lshlrev_b32_e32 v214, 16, v190
	v_and_b32_e32 v215, 0xffff0000, v190
	v_lshlrev_b32_e32 v216, 16, v191
	v_and_b32_e32 v217, 0xffff0000, v191
	v_pk_mul_f32 v[218:219], v[210:211], v[208:209]
	v_pk_mul_f32 v[220:221], v[212:213], v[208:209]
	v_pk_mul_f32 v[222:223], v[214:215], v[208:209]
	v_pk_mul_f32 v[226:227], v[216:217], v[208:209]
	v_exp_f32_e32 v84, v84
	v_exp_f32_e32 v85, v85
	v_exp_f32_e32 v86, v86
	v_exp_f32_e32 v87, v87
	v_exp_f32_e32 v80, v80
	v_exp_f32_e32 v81, v81
	v_exp_f32_e32 v82, v82
	v_exp_f32_e32 v83, v83
	v_exp_f32_e32 v218, v218
	v_exp_f32_e32 v219, v219
	v_exp_f32_e32 v220, v220
	v_exp_f32_e32 v221, v221
	v_exp_f32_e32 v222, v222
	v_exp_f32_e32 v223, v223
	v_exp_f32_e32 v226, v226
	v_exp_f32_e32 v227, v227
	v_or_b32_e32 v170, 48, v168
	v_mad_i64_i32 v[172:173], s[30:31], v170, s52, v[160:161]
	v_mad_i64_i32 v[174:175], s[30:31], v170, s66, v[172:173]
	v_lshl_add_u64 v[174:175], v[174:175], 0, v[158:159]
	v_add_co_u32_e32 v174, vcc, s67, v174
	s_nop 1
	v_addc_co_u32_e32 v175, vcc, 0, v175, vcc
	v_pk_add_f32 v[84:85], v[84:85], 1.0 op_sel_hi:[1,0]
	v_pk_add_f32 v[86:87], v[86:87], 1.0 op_sel_hi:[1,0]
	v_pk_add_f32 v[80:81], v[80:81], 1.0 op_sel_hi:[1,0]
	v_pk_add_f32 v[82:83], v[82:83], 1.0 op_sel_hi:[1,0]
	v_pk_add_f32 v[218:219], v[218:219], 1.0 op_sel_hi:[1,0]
	v_pk_add_f32 v[220:221], v[220:221], 1.0 op_sel_hi:[1,0]
	v_pk_add_f32 v[222:223], v[222:223], 1.0 op_sel_hi:[1,0]
	v_pk_add_f32 v[226:227], v[226:227], 1.0 op_sel_hi:[1,0]
	v_pk_mul_f32 v[218:219], v[218:219], v[84:85]
	v_pk_mul_f32 v[220:221], v[220:221], v[86:87]
	v_pk_mul_f32 v[222:223], v[222:223], v[80:81]
	v_pk_mul_f32 v[226:227], v[226:227], v[82:83]
	v_rcp_f32_e32 v218, v218
	v_rcp_f32_e32 v219, v219
	v_rcp_f32_e32 v220, v220
	v_rcp_f32_e32 v221, v221
	v_rcp_f32_e32 v222, v222
	v_rcp_f32_e32 v223, v223
	v_rcp_f32_e32 v226, v226
	v_rcp_f32_e32 v227, v227
	v_pk_mul_f32 v[92:93], v[92:93], v[210:211]
	v_pk_mul_f32 v[94:95], v[94:95], v[212:213]
	v_pk_mul_f32 v[88:89], v[88:89], v[214:215]
	v_pk_mul_f32 v[90:91], v[90:91], v[216:217]
	v_pk_mul_f32 v[92:93], v[92:93], v[218:219]
	v_pk_mul_f32 v[94:95], v[94:95], v[220:221]
	v_pk_mul_f32 v[88:89], v[88:89], v[222:223]
	v_pk_mul_f32 v[90:91], v[90:91], v[226:227]
	v_cvt_pk_bf16_f32 v80, v92, v93
	v_cvt_pk_bf16_f32 v81, v94, v95
	v_cvt_pk_bf16_f32 v82, v88, v89
	v_cvt_pk_bf16_f32 v83, v90, v91
	global_store_dwordx4 v[174:175], v[80:83], off offset:2048
	s_waitcnt vmcnt(7)
	v_pk_add_f32 v[76:77], v[76:77], v[28:29]
	v_pk_add_f32 v[78:79], v[78:79], v[30:31]
	v_pk_add_f32 v[72:73], v[72:73], v[24:25]
	v_pk_add_f32 v[74:75], v[74:75], v[26:27]
	v_pk_add_f32 v[68:69], v[68:69], v[20:21]
	v_pk_add_f32 v[70:71], v[70:71], v[22:23]
	v_pk_add_f32 v[64:65], v[64:65], v[16:17]
	v_pk_add_f32 v[66:67], v[66:67], v[18:19]
	v_pk_mul_f32 v[68:69], v[68:69], v[208:209]
	v_pk_mul_f32 v[70:71], v[70:71], v[208:209]
	v_pk_mul_f32 v[64:65], v[64:65], v[208:209]
	v_pk_mul_f32 v[66:67], v[66:67], v[208:209]
	v_lshlrev_b32_e32 v210, 16, v192
	v_and_b32_e32 v211, 0xffff0000, v192
	v_lshlrev_b32_e32 v212, 16, v193
	v_and_b32_e32 v213, 0xffff0000, v193
	v_lshlrev_b32_e32 v214, 16, v194
	v_and_b32_e32 v215, 0xffff0000, v194
	v_lshlrev_b32_e32 v216, 16, v195
	v_and_b32_e32 v217, 0xffff0000, v195
	v_pk_mul_f32 v[218:219], v[210:211], v[208:209]
	v_pk_mul_f32 v[220:221], v[212:213], v[208:209]
	v_pk_mul_f32 v[222:223], v[214:215], v[208:209]
	v_pk_mul_f32 v[226:227], v[216:217], v[208:209]
	v_exp_f32_e32 v68, v68
	v_exp_f32_e32 v69, v69
	v_exp_f32_e32 v70, v70
	v_exp_f32_e32 v71, v71
	v_exp_f32_e32 v64, v64
	v_exp_f32_e32 v65, v65
	v_exp_f32_e32 v66, v66
	v_exp_f32_e32 v67, v67
	v_exp_f32_e32 v218, v218
	v_exp_f32_e32 v219, v219
	v_exp_f32_e32 v220, v220
	v_exp_f32_e32 v221, v221
	v_exp_f32_e32 v222, v222
	v_exp_f32_e32 v223, v223
	v_exp_f32_e32 v226, v226
	v_exp_f32_e32 v227, v227
	v_add_u32_e32 v170, 0x80, v168
	v_mad_i64_i32 v[172:173], s[30:31], v170, s52, v[160:161]
	v_mad_i64_i32 v[174:175], s[30:31], v170, s66, v[172:173]
	v_lshl_add_u64 v[174:175], v[174:175], 0, v[158:159]
	v_add_co_u32_e32 v174, vcc, s67, v174
	s_nop 1
	v_addc_co_u32_e32 v175, vcc, 0, v175, vcc
	v_pk_add_f32 v[68:69], v[68:69], 1.0 op_sel_hi:[1,0]
	v_pk_add_f32 v[70:71], v[70:71], 1.0 op_sel_hi:[1,0]
	v_pk_add_f32 v[64:65], v[64:65], 1.0 op_sel_hi:[1,0]
	v_pk_add_f32 v[66:67], v[66:67], 1.0 op_sel_hi:[1,0]
	v_pk_add_f32 v[218:219], v[218:219], 1.0 op_sel_hi:[1,0]
	v_pk_add_f32 v[220:221], v[220:221], 1.0 op_sel_hi:[1,0]
	v_pk_add_f32 v[222:223], v[222:223], 1.0 op_sel_hi:[1,0]
	v_pk_add_f32 v[226:227], v[226:227], 1.0 op_sel_hi:[1,0]
	v_pk_mul_f32 v[218:219], v[218:219], v[68:69]
	v_pk_mul_f32 v[220:221], v[220:221], v[70:71]
	v_pk_mul_f32 v[222:223], v[222:223], v[64:65]
	v_pk_mul_f32 v[226:227], v[226:227], v[66:67]
	v_rcp_f32_e32 v218, v218
	v_rcp_f32_e32 v219, v219
	v_rcp_f32_e32 v220, v220
	v_rcp_f32_e32 v221, v221
	v_rcp_f32_e32 v222, v222
	v_rcp_f32_e32 v223, v223
	v_rcp_f32_e32 v226, v226
	v_rcp_f32_e32 v227, v227
	v_pk_mul_f32 v[76:77], v[76:77], v[210:211]
	v_pk_mul_f32 v[78:79], v[78:79], v[212:213]
	v_pk_mul_f32 v[72:73], v[72:73], v[214:215]
	v_pk_mul_f32 v[74:75], v[74:75], v[216:217]
	v_pk_mul_f32 v[76:77], v[76:77], v[218:219]
	v_pk_mul_f32 v[78:79], v[78:79], v[220:221]
	v_pk_mul_f32 v[72:73], v[72:73], v[222:223]
	v_pk_mul_f32 v[74:75], v[74:75], v[226:227]
	v_cvt_pk_bf16_f32 v64, v76, v77
	v_cvt_pk_bf16_f32 v65, v78, v79
	v_cvt_pk_bf16_f32 v66, v72, v73
	v_cvt_pk_bf16_f32 v67, v74, v75
	global_store_dwordx4 v[174:175], v[64:67], off offset:2048
	s_waitcnt vmcnt(7)
; __device__ __forceinline__ unsigned cvt_pk_bf16(float lo, float hi) { unsigned r; asm volatile("v_cvt_pk_bf16_f32 %0, %1, %2" : "=v"(r) : "v"(lo), "v"(hi)); return r; }
; __device__ __forceinline__ float bflo(unsigned w) { return __uint_as_float(w << 16); }
; __device__ __forceinline__ float bfhi(unsigned w) { return __uint_as_float(w & 0xffff0000u); }
; __device__ __forceinline__ float silu_f(float z) { return z / (1.0f + __expf(-z)); }
; __device__ __forceinline__ float sigmoid_f(float z) { return 1.0f / (1.0f + __expf(-z)); }
;     __device__ __forceinline__ void operator()(const AccT& acc, const Unit& u, int wr, int wc, int fr, int fq) const {
;     ...
;                 const int row = u.pm * 256 + ai * 128 + wr * 64 + m * 16 + fr;
;                 const u32x4 z = *(const u32x4*)(PROJ + (size_t)row * PP + C_ZS + lc);
;                 const f32x4 l0 = acc[ai][0][m][0] + bl0, l1 = acc[ai][0][m][1] + bl1, g0 = acc[ai][1][m][0] + bg0, g1 = acc[ai][1][m][1] + bg1;
;                 float o[8];
;                 o[0] = l0[0] * sigmoid_f(g0[0]) * silu_f(bflo(z.x)); o[1] = l0[1] * sigmoid_f(g0[1]) * silu_f(bfhi(z.x));
;                 o[2] = l0[2] * sigmoid_f(g0[2]) * silu_f(bflo(z.y)); o[3] = l0[3] * sigmoid_f(g0[3]) * silu_f(bfhi(z.y));
;                 o[4] = l1[0] * sigmoid_f(g1[0]) * silu_f(bflo(z.z)); o[5] = l1[1] * sigmoid_f(g1[1]) * silu_f(bfhi(z.z));
;                 o[6] = l1[2] * sigmoid_f(g1[2]) * silu_f(bflo(z.w)); o[7] = l1[3] * sigmoid_f(g1[3]) * silu_f(bfhi(z.w));
;                 u32x4 w; w.x = cvt_pk_bf16(o[0], o[1]); w.y = cvt_pk_bf16(o[2], o[3]); w.z = cvt_pk_bf16(o[4], o[5]); w.w = cvt_pk_bf16(o[6], o[7]);
;                 *(u32x4*)(OCAT + (size_t)row * 2048 + 1024 + lc) = w;
	v_pk_add_f32 v[60:61], v[60:61], v[28:29]
	v_pk_add_f32 v[62:63], v[62:63], v[30:31]
	v_pk_add_f32 v[56:57], v[56:57], v[24:25]
	v_pk_add_f32 v[58:59], v[58:59], v[26:27]
	v_pk_add_f32 v[52:53], v[52:53], v[20:21]
	v_pk_add_f32 v[54:55], v[54:55], v[22:23]
	v_pk_add_f32 v[48:49], v[48:49], v[16:17]
	v_pk_add_f32 v[50:51], v[50:51], v[18:19]
	v_pk_mul_f32 v[52:53], v[52:53], v[208:209]
	v_pk_mul_f32 v[54:55], v[54:55], v[208:209]
	v_pk_mul_f32 v[48:49], v[48:49], v[208:209]
	v_pk_mul_f32 v[50:51], v[50:51], v[208:209]
	v_lshlrev_b32_e32 v210, 16, v196
	v_and_b32_e32 v211, 0xffff0000, v196
	v_lshlrev_b32_e32 v212, 16, v197
	v_and_b32_e32 v213, 0xffff0000, v197
	v_lshlrev_b32_e32 v214, 16, v198
	v_and_b32_e32 v215, 0xffff0000, v198
	v_lshlrev_b32_e32 v216, 16, v199
	v_and_b32_e32 v217, 0xffff0000, v199
	v_pk_mul_f32 v[218:219], v[210:211], v[208:209]
	v_pk_mul_f32 v[220:221], v[212:213], v[208:209]
	v_pk_mul_f32 v[222:223], v[214:215], v[208:209]
	v_pk_mul_f32 v[226:227], v[216:217], v[208:209]
	v_exp_f32_e32 v52, v52
	v_exp_f32_e32 v53, v53
	v_exp_f32_e32 v54, v54
	v_exp_f32_e32 v55, v55
	v_exp_f32_e32 v48, v48
	v_exp_f32_e32 v49, v49
	v_exp_f32_e32 v50, v50
	v_exp_f32_e32 v51, v51
	v_exp_f32_e32 v218, v218
	v_exp_f32_e32 v219, v219
	v_exp_f32_e32 v220, v220
	v_exp_f32_e32 v221, v221
	v_exp_f32_e32 v222, v222
	v_exp_f32_e32 v223, v223
	v_exp_f32_e32 v226, v226
	v_exp_f32_e32 v227, v227
	v_add_u32_e32 v170, 0x90, v168
	v_mad_i64_i32 v[172:173], s[30:31], v170, s52, v[160:161]
	v_mad_i64_i32 v[174:175], s[30:31], v170, s66, v[172:173]
	v_lshl_add_u64 v[174:175], v[174:175], 0, v[158:159]
	v_add_co_u32_e32 v174, vcc, s67, v174
	s_nop 1
	v_addc_co_u32_e32 v175, vcc, 0, v175, vcc
	v_pk_add_f32 v[52:53], v[52:53], 1.0 op_sel_hi:[1,0]
	v_pk_add_f32 v[54:55], v[54:55], 1.0 op_sel_hi:[1,0]
	v_pk_add_f32 v[48:49], v[48:49], 1.0 op_sel_hi:[1,0]
	v_pk_add_f32 v[50:51], v[50:51], 1.0 op_sel_hi:[1,0]
	v_pk_add_f32 v[218:219], v[218:219], 1.0 op_sel_hi:[1,0]
	v_pk_add_f32 v[220:221], v[220:221], 1.0 op_sel_hi:[1,0]
	v_pk_add_f32 v[222:223], v[222:223], 1.0 op_sel_hi:[1,0]
	v_pk_add_f32 v[226:227], v[226:227], 1.0 op_sel_hi:[1,0]
	v_pk_mul_f32 v[218:219], v[218:219], v[52:53]
	v_pk_mul_f32 v[220:221], v[220:221], v[54:55]
	v_pk_mul_f32 v[222:223], v[222:223], v[48:49]
	v_pk_mul_f32 v[226:227], v[226:227], v[50:51]
	v_rcp_f32_e32 v218, v218
	v_rcp_f32_e32 v219, v219
	v_rcp_f32_e32 v220, v220
	v_rcp_f32_e32 v221, v221
	v_rcp_f32_e32 v222, v222
	v_rcp_f32_e32 v223, v223
	v_rcp_f32_e32 v226, v226
	v_rcp_f32_e32 v227, v227
	v_pk_mul_f32 v[60:61], v[60:61], v[210:211]
	v_pk_mul_f32 v[62:63], v[62:63], v[212:213]
	v_pk_mul_f32 v[56:57], v[56:57], v[214:215]
	v_pk_mul_f32 v[58:59], v[58:59], v[216:217]
	v_pk_mul_f32 v[60:61], v[60:61], v[218:219]
	v_pk_mul_f32 v[62:63], v[62:63], v[220:221]
	v_pk_mul_f32 v[56:57], v[56:57], v[222:223]
	v_pk_mul_f32 v[58:59], v[58:59], v[226:227]
	v_cvt_pk_bf16_f32 v48, v60, v61
	v_cvt_pk_bf16_f32 v49, v62, v63
	v_cvt_pk_bf16_f32 v50, v56, v57
	v_cvt_pk_bf16_f32 v51, v58, v59
	global_store_dwordx4 v[174:175], v[48:51], off offset:2048
	s_waitcnt vmcnt(7)
	v_pk_add_f32 v[44:45], v[44:45], v[28:29]
	v_pk_add_f32 v[46:47], v[46:47], v[30:31]
	v_pk_add_f32 v[40:41], v[40:41], v[24:25]
	v_pk_add_f32 v[42:43], v[42:43], v[26:27]
	v_pk_add_f32 v[36:37], v[36:37], v[20:21]
	v_pk_add_f32 v[38:39], v[38:39], v[22:23]
	v_pk_add_f32 v[32:33], v[32:33], v[16:17]
	v_pk_add_f32 v[34:35], v[34:35], v[18:19]
	v_pk_mul_f32 v[36:37], v[36:37], v[208:209]
	v_pk_mul_f32 v[38:39], v[38:39], v[208:209]
	v_pk_mul_f32 v[32:33], v[32:33], v[208:209]
	v_pk_mul_f32 v[34:35], v[34:35], v[208:209]
	v_lshlrev_b32_e32 v210, 16, v200
	v_and_b32_e32 v211, 0xffff0000, v200
	v_lshlrev_b32_e32 v212, 16, v201
	v_and_b32_e32 v213, 0xffff0000, v201
	v_lshlrev_b32_e32 v214, 16, v202
	v_and_b32_e32 v215, 0xffff0000, v202
	v_lshlrev_b32_e32 v216, 16, v203
	v_and_b32_e32 v217, 0xffff0000, v203
	v_pk_mul_f32 v[218:219], v[210:211], v[208:209]
	v_pk_mul_f32 v[220:221], v[212:213], v[208:209]
	v_pk_mul_f32 v[222:223], v[214:215], v[208:209]
	v_pk_mul_f32 v[226:227], v[216:217], v[208:209]
	v_exp_f32_e32 v36, v36
	v_exp_f32_e32 v37, v37
	v_exp_f32_e32 v38, v38
	v_exp_f32_e32 v39, v39
	v_exp_f32_e32 v32, v32
	v_exp_f32_e32 v33, v33
	v_exp_f32_e32 v34, v34
	v_exp_f32_e32 v35, v35
	v_exp_f32_e32 v218, v218
	v_exp_f32_e32 v219, v219
	v_exp_f32_e32 v220, v220
	v_exp_f32_e32 v221, v221
	v_exp_f32_e32 v222, v222
	v_exp_f32_e32 v223, v223
	v_exp_f32_e32 v226, v226
	v_exp_f32_e32 v227, v227
	v_add_u32_e32 v170, 0xa0, v168
	v_mad_i64_i32 v[172:173], s[30:31], v170, s52, v[160:161]
	v_mad_i64_i32 v[174:175], s[30:31], v170, s66, v[172:173]
	v_lshl_add_u64 v[174:175], v[174:175], 0, v[158:159]
	v_add_co_u32_e32 v174, vcc, s67, v174
	s_nop 1
	v_addc_co_u32_e32 v175, vcc, 0, v175, vcc
	v_pk_add_f32 v[36:37], v[36:37], 1.0 op_sel_hi:[1,0]
	v_pk_add_f32 v[38:39], v[38:39], 1.0 op_sel_hi:[1,0]
	v_pk_add_f32 v[32:33], v[32:33], 1.0 op_sel_hi:[1,0]
	v_pk_add_f32 v[34:35], v[34:35], 1.0 op_sel_hi:[1,0]
	v_pk_add_f32 v[218:219], v[218:219], 1.0 op_sel_hi:[1,0]
	v_pk_add_f32 v[220:221], v[220:221], 1.0 op_sel_hi:[1,0]
	v_pk_add_f32 v[222:223], v[222:223], 1.0 op_sel_hi:[1,0]
	v_pk_add_f32 v[226:227], v[226:227], 1.0 op_sel_hi:[1,0]
	v_pk_mul_f32 v[218:219], v[218:219], v[36:37]
	v_pk_mul_f32 v[220:221], v[220:221], v[38:39]
	v_pk_mul_f32 v[222:223], v[222:223], v[32:33]
	v_pk_mul_f32 v[226:227], v[226:227], v[34:35]
	v_rcp_f32_e32 v218, v218
	v_rcp_f32_e32 v219, v219
	v_rcp_f32_e32 v220, v220
	v_rcp_f32_e32 v221, v221
	v_rcp_f32_e32 v222, v222
	v_rcp_f32_e32 v223, v223
	v_rcp_f32_e32 v226, v226
	v_rcp_f32_e32 v227, v227
	v_pk_mul_f32 v[44:45], v[44:45], v[210:211]
	v_pk_mul_f32 v[46:47], v[46:47], v[212:213]
	v_pk_mul_f32 v[40:41], v[40:41], v[214:215]
	v_pk_mul_f32 v[42:43], v[42:43], v[216:217]
	v_pk_mul_f32 v[44:45], v[44:45], v[218:219]
	v_pk_mul_f32 v[46:47], v[46:47], v[220:221]
	v_pk_mul_f32 v[40:41], v[40:41], v[222:223]
	v_pk_mul_f32 v[42:43], v[42:43], v[226:227]
	v_cvt_pk_bf16_f32 v32, v44, v45
	v_cvt_pk_bf16_f32 v33, v46, v47
	v_cvt_pk_bf16_f32 v34, v40, v41
	v_cvt_pk_bf16_f32 v35, v42, v43
	global_store_dwordx4 v[174:175], v[32:35], off offset:2048
	s_waitcnt vmcnt(7)
; __device__ __forceinline__ unsigned cvt_pk_bf16(float lo, float hi) { unsigned r; asm volatile("v_cvt_pk_bf16_f32 %0, %1, %2" : "=v"(r) : "v"(lo), "v"(hi)); return r; }
; __device__ __forceinline__ float bflo(unsigned w) { return __uint_as_float(w << 16); }
; __device__ __forceinline__ float bfhi(unsigned w) { return __uint_as_float(w & 0xffff0000u); }
; __device__ __forceinline__ float silu_f(float z) { return z / (1.0f + __expf(-z)); }
; __device__ __forceinline__ float sigmoid_f(float z) { return 1.0f / (1.0f + __expf(-z)); }
;     __device__ __forceinline__ void operator()(const AccT& acc, const Unit& u, int wr, int wc, int fr, int fq) const {
;     ...
;                 const int row = u.pm * 256 + ai * 128 + wr * 64 + m * 16 + fr;
;                 const u32x4 z = *(const u32x4*)(PROJ + (size_t)row * PP + C_ZS + lc);
;                 const f32x4 l0 = acc[ai][0][m][0] + bl0, l1 = acc[ai][0][m][1] + bl1, g0 = acc[ai][1][m][0] + bg0, g1 = acc[ai][1][m][1] + bg1;
;                 float o[8];
;                 o[0] = l0[0] * sigmoid_f(g0[0]) * silu_f(bflo(z.x)); o[1] = l0[1] * sigmoid_f(g0[1]) * silu_f(bfhi(z.x));
;                 o[2] = l0[2] * sigmoid_f(g0[2]) * silu_f(bflo(z.y)); o[3] = l0[3] * sigmoid_f(g0[3]) * silu_f(bfhi(z.y));
;                 o[4] = l1[0] * sigmoid_f(g1[0]) * silu_f(bflo(z.z)); o[5] = l1[1] * sigmoid_f(g1[1]) * silu_f(bfhi(z.z));
;                 o[6] = l1[2] * sigmoid_f(g1[2]) * silu_f(bflo(z.w)); o[7] = l1[3] * sigmoid_f(g1[3]) * silu_f(bfhi(z.w));
;                 u32x4 w; w.x = cvt_pk_bf16(o[0], o[1]); w.y = cvt_pk_bf16(o[2], o[3]); w.z = cvt_pk_bf16(o[4], o[5]); w.w = cvt_pk_bf16(o[6], o[7]);
;                 *(u32x4*)(OCAT + (size_t)row * 2048 + 1024 + lc) = w;
;                 if (m == 3) asm volatile("" ::: "memory");
;             }
	v_pk_add_f32 v[12:13], v[12:13], v[28:29]
	v_pk_add_f32 v[14:15], v[14:15], v[30:31]
	v_pk_add_f32 v[8:9], v[8:9], v[24:25]
	v_pk_add_f32 v[10:11], v[10:11], v[26:27]
	v_pk_add_f32 v[4:5], v[4:5], v[20:21]
	v_pk_add_f32 v[6:7], v[6:7], v[22:23]
	v_pk_add_f32 v[0:1], v[0:1], v[16:17]
	v_pk_add_f32 v[2:3], v[2:3], v[18:19]
	v_pk_mul_f32 v[4:5], v[4:5], v[208:209]
	v_pk_mul_f32 v[6:7], v[6:7], v[208:209]
	v_pk_mul_f32 v[0:1], v[0:1], v[208:209]
	v_pk_mul_f32 v[2:3], v[2:3], v[208:209]
	v_lshlrev_b32_e32 v210, 16, v204
	v_and_b32_e32 v211, 0xffff0000, v204
	v_lshlrev_b32_e32 v212, 16, v205
	v_and_b32_e32 v213, 0xffff0000, v205
	v_lshlrev_b32_e32 v214, 16, v206
	v_and_b32_e32 v215, 0xffff0000, v206
	v_lshlrev_b32_e32 v216, 16, v207
	v_and_b32_e32 v217, 0xffff0000, v207
	v_pk_mul_f32 v[218:219], v[210:211], v[208:209]
	v_pk_mul_f32 v[220:221], v[212:213], v[208:209]
	v_pk_mul_f32 v[222:223], v[214:215], v[208:209]
	v_pk_mul_f32 v[226:227], v[216:217], v[208:209]
	v_exp_f32_e32 v4, v4
	v_exp_f32_e32 v5, v5
	v_exp_f32_e32 v6, v6
	v_exp_f32_e32 v7, v7
	v_exp_f32_e32 v0, v0
	v_exp_f32_e32 v1, v1
	v_exp_f32_e32 v2, v2
	v_exp_f32_e32 v3, v3
	v_exp_f32_e32 v218, v218
	v_exp_f32_e32 v219, v219
	v_exp_f32_e32 v220, v220
	v_exp_f32_e32 v221, v221
	v_exp_f32_e32 v222, v222
	v_exp_f32_e32 v223, v223
	v_exp_f32_e32 v226, v226
	v_exp_f32_e32 v227, v227
	v_add_u32_e32 v170, 0xb0, v168
	v_mad_i64_i32 v[172:173], s[30:31], v170, s52, v[160:161]
	v_mad_i64_i32 v[174:175], s[30:31], v170, s66, v[172:173]
	v_lshl_add_u64 v[174:175], v[174:175], 0, v[158:159]
	v_add_co_u32_e32 v174, vcc, 0xca00000, v174
	s_nop 1
	v_addc_co_u32_e32 v175, vcc, 0, v175, vcc
	v_pk_add_f32 v[4:5], v[4:5], 1.0 op_sel_hi:[1,0]
	v_pk_add_f32 v[6:7], v[6:7], 1.0 op_sel_hi:[1,0]
	v_pk_add_f32 v[0:1], v[0:1], 1.0 op_sel_hi:[1,0]
	v_pk_add_f32 v[2:3], v[2:3], 1.0 op_sel_hi:[1,0]
	v_pk_add_f32 v[218:219], v[218:219], 1.0 op_sel_hi:[1,0]
	v_pk_add_f32 v[220:221], v[220:221], 1.0 op_sel_hi:[1,0]
	v_pk_add_f32 v[222:223], v[222:223], 1.0 op_sel_hi:[1,0]
	v_pk_add_f32 v[226:227], v[226:227], 1.0 op_sel_hi:[1,0]
	v_pk_mul_f32 v[218:219], v[218:219], v[4:5]
	v_pk_mul_f32 v[220:221], v[220:221], v[6:7]
	v_pk_mul_f32 v[222:223], v[222:223], v[0:1]
	v_pk_mul_f32 v[226:227], v[226:227], v[2:3]
	v_rcp_f32_e32 v218, v218
	v_rcp_f32_e32 v219, v219
	v_rcp_f32_e32 v220, v220
	v_rcp_f32_e32 v221, v221
	v_rcp_f32_e32 v222, v222
	v_rcp_f32_e32 v223, v223
	v_rcp_f32_e32 v226, v226
	v_rcp_f32_e32 v227, v227
	v_pk_mul_f32 v[12:13], v[12:13], v[210:211]
	v_pk_mul_f32 v[14:15], v[14:15], v[212:213]
	v_pk_mul_f32 v[8:9], v[8:9], v[214:215]
	v_pk_mul_f32 v[10:11], v[10:11], v[216:217]
	v_pk_mul_f32 v[12:13], v[12:13], v[218:219]
	v_pk_mul_f32 v[14:15], v[14:15], v[220:221]
	v_pk_mul_f32 v[8:9], v[8:9], v[222:223]
	v_pk_mul_f32 v[10:11], v[10:11], v[226:227]
	v_cvt_pk_bf16_f32 v0, v12, v13
	v_cvt_pk_bf16_f32 v1, v14, v15
	v_cvt_pk_bf16_f32 v2, v8, v9
	v_cvt_pk_bf16_f32 v3, v10, v11
	s_mov_b64 s[30:31], -1
	global_store_dwordx4 v[174:175], v[0:3], off offset:2048
	s_andn2_b64 vcc, exec, s[4:5]
	s_cbranch_vccnz .LBB0_598
	s_andn2_b64 vcc, exec, s[8:9]
	s_cbranch_vccnz .LBB0_597
	s_barrier
	s_branch .LBB0_597
